# ADIFF inner loop: drop compiler vmcnt(0) before V tr-reads (counted vmcnt(4) at chunk top already covers it)
# speedup vs baseline: 1.0259x; 1.0259x over previous
; #define LAS __attribute__((address_space(3)))
; __device__ __forceinline__ void diff_attn_phase(const Params& p, LAS unsigned char* lds) {
;     ...
;                 const LAS unsigned char* Ku = Ksb + u * 8192; const LAS unsigned char* Vu = Vsb + u * 8192;
;                 int kxl = kx, vb0l = vb0, vb1l = vb1; asm volatile("" : "+v"(kxl), "+v"(vb0l), "+v"(vb1l));
;                 bf16x8 kf[4];
; #pragma unroll
;                 for (int ks = 0; ks < 4; ++ks) kf[ks] = *(const LAS bf16x8*)(Ku + kbase + (kxl ^ (32 * ks)));
;                 bf16x8 P[2][2];
; #pragma unroll
;                 for (int r = 0; r < 2; ++r) {
;                     f32x16 S;
; #pragma unroll
;                     for (int i = 0; i < 16; ++i) S[i] = 0.f;
; #pragma unroll
;                     for (int ks = 0; ks < 4; ++ks) S = __builtin_amdgcn_mfma_f32_32x32x16_bf16(kf[ks], qf[r][ks], S, 0, 0, 0);
;                     S = __builtin_amdgcn_mfma_f32_32x32x16_bf16(kone, qm[r], S, 0, 0, 0);
; #pragma unroll
;                     for (int i = 0; i < 16; ++i) S[i] = __builtin_amdgcn_exp2f(S[i]);
;                     l[r] += sum16(S);
;                     P[r][0] = pack8(S, 0); P[r][1] = pack8(S, 8);
;                 }
; #pragma unroll
;                 for (int t = 0; t < 4; ++t) {
;                     const LAS unsigned char* a0 = Vu + (vb0l ^ (64 * t)); const LAS unsigned char* a1 = Vu + (vb1l ^ (64 * t));
;                     const bf16x8 v0 = tr_pair(a0, a1), v1 = tr_pair(a0 + 4096, a1 + 4096);
;                     O[0][t] = __builtin_amdgcn_mfma_f32_32x32x16_bf16(v0, P[0][0], O[0][t], 0, 0, 0);
;                     O[1][t] = __builtin_amdgcn_mfma_f32_32x32x16_bf16(v0, P[1][0], O[1][t], 0, 0, 0);
;                     O[0][t] = __builtin_amdgcn_mfma_f32_32x32x16_bf16(v1, P[0][1], O[0][t], 0, 0, 0);
;                     O[1][t] = __builtin_amdgcn_mfma_f32_32x32x16_bf16(v1, P[1][1], O[1][t], 0, 0, 0);
;                 }
.LBB0_48:
	v_mov_b32_e32 v208, v247
	v_mov_b32_e32 v209, v246
	v_mov_b32_e32 v210, v248
	v_add_u32_e32 v211, s47, v1
	s_movk_i32 s2, 0x60
	v_add_u32_e32 v130, v211, v209
	ds_read_b128 v[130:133], v130
	v_xad_u32 v214, v209, 32, v211
	ds_read_b128 v[214:217], v214
	v_xad_u32 v218, v209, 64, v211
	s_waitcnt lgkmcnt(0)
	v_mfma_f32_32x32x16_bf16 v[146:161], v[130:133], v[166:169], 0
	v_xad_u32 v209, v209, s2, v211
	s_add_i32 s47, s37, s47
	v_add_u32_e32 v226, s47, v208
	v_add_u32_e32 v228, s47, v210
	v_xad_u32 v237, v208, 64, s47
	v_xad_u32 v250, v210, 64, s47
	v_xor_b32_e32 v211, 0x80, v210
	v_mfma_f32_32x32x16_bf16 v[130:145], v[130:133], v[182:185], 0
	v_add_u32_e32 v238, s47, v211
	v_mfma_f32_32x32x16_bf16 v[146:161], v[214:217], v[170:173], v[146:161]
	v_mfma_f32_32x32x16_bf16 v[130:145], v[214:217], v[186:189], v[130:145]
	ds_read_b128 v[214:217], v218
	s_waitcnt lgkmcnt(0)
	v_mfma_f32_32x32x16_bf16 v[146:161], v[214:217], v[174:177], v[146:161]
	v_mfma_f32_32x32x16_bf16 v[130:145], v[214:217], v[190:193], v[130:145]
	ds_read_b128 v[214:217], v209
	s_nop 0
	ds_read_b64_tr_b16 v[222:223], v226 offset:16384
	ds_read_b64_tr_b16 v[224:225], v228 offset:16384
	v_xor_b32_e32 v209, 0x80, v208
	v_add_u32_e32 v251, s47, v209
	v_xor_b32_e32 v208, 0xc0, v208
	v_xor_b32_e32 v209, 0xc0, v210
	v_add_u32_e32 v239, s47, v208
	s_waitcnt lgkmcnt(2)
	v_mfma_f32_32x32x16_bf16 v[146:161], v[214:217], v[178:181], v[146:161]
	v_add_u32_e32 v234, s47, v209
	s_movk_i32 s47, 0x2000
	v_mfma_f32_32x32x16_bf16 v[130:145], v[214:217], v[194:197], v[130:145]
	v_mfma_f32_32x32x16_bf16 v[146:161], v[162:165], v[198:201], v[146:161]
	v_mfma_f32_32x32x16_bf16 v[130:145], v[162:165], v[202:205], v[130:145]
	s_nop 10
	v_exp_f32_e32 v215, v146
	v_exp_f32_e32 v219, v147
	v_exp_f32_e32 v217, v148
	v_exp_f32_e32 v221, v149
	v_exp_f32_e32 v147, v150
	v_exp_f32_e32 v151, v151
	v_exp_f32_e32 v149, v152
	v_exp_f32_e32 v153, v153
	v_exp_f32_e32 v214, v130
	v_exp_f32_e32 v218, v131
	v_exp_f32_e32 v216, v132
	v_exp_f32_e32 v220, v133
	v_exp_f32_e32 v146, v134
	v_exp_f32_e32 v150, v135
	v_exp_f32_e32 v148, v136
	v_exp_f32_e32 v152, v137
	v_cvt_pk_bf16_f32 v130, v215, v219
	v_cvt_pk_bf16_f32 v131, v217, v221
	v_cvt_pk_bf16_f32 v132, v147, v151
	v_cvt_pk_bf16_f32 v133, v149, v153
	v_cvt_pk_bf16_f32 v134, v214, v218
	v_cvt_pk_bf16_f32 v135, v216, v220
	v_cvt_pk_bf16_f32 v136, v146, v150
	v_cvt_pk_bf16_f32 v137, v148, v152
	s_waitcnt lgkmcnt(0)
	v_mfma_f32_32x32x16_bf16 v[114:129], v[222:225], v[130:133], v[114:129]
	v_exp_f32_e32 v227, v157
	v_exp_f32_e32 v157, v158
	v_exp_f32_e32 v229, v159
	v_exp_f32_e32 v159, v160
	v_exp_f32_e32 v158, v144
	v_exp_f32_e32 v160, v145
	v_exp_f32_e32 v161, v161
	v_mfma_f32_32x32x16_bf16 v[50:65], v[222:225], v[134:137], v[50:65]
	ds_read_b64_tr_b16 v[222:223], v237 offset:16384
	ds_read_b64_tr_b16 v[224:225], v250 offset:16384
	s_waitcnt lgkmcnt(0)
	v_mfma_f32_32x32x16_bf16 v[98:113], v[222:225], v[130:133], v[98:113]
	v_mfma_f32_32x32x16_bf16 v[34:49], v[222:225], v[134:137], v[34:49]
	ds_read_b64_tr_b16 v[222:223], v251 offset:16384
	ds_read_b64_tr_b16 v[224:225], v238 offset:16384
	ds_read_b64_tr_b16 v[208:209], v239 offset:16384
	ds_read_b64_tr_b16 v[210:211], v234 offset:16384
	ds_read_b64_tr_b16 v[230:231], v226 offset:20480
	ds_read_b64_tr_b16 v[232:233], v228 offset:20480
	v_exp_f32_e32 v226, v141
	v_exp_f32_e32 v228, v143
	s_waitcnt lgkmcnt(4)
	v_mfma_f32_32x32x16_bf16 v[82:97], v[222:225], v[130:133], v[82:97]
	v_mfma_f32_32x32x16_bf16 v[18:33], v[222:225], v[134:137], v[18:33]
	v_exp_f32_e32 v225, v155
	v_exp_f32_e32 v155, v156
	v_exp_f32_e32 v156, v142
	v_cndmask_b32_e64 v142, 0, 1, s[42:43]
	v_exp_f32_e32 v223, v154
	v_exp_f32_e32 v222, v138
	v_exp_f32_e32 v224, v139
	s_waitcnt lgkmcnt(2)
	v_mfma_f32_32x32x16_bf16 v[66:81], v[208:211], v[130:133], v[66:81]
	v_exp_f32_e32 v154, v140
	ds_read_b64_tr_b16 v[138:139], v251 offset:20480
	ds_read_b64_tr_b16 v[140:141], v238 offset:20480
	v_cmp_ne_u32_e32 vcc, 1, v142
	ds_read_b64_tr_b16 v[142:143], v239 offset:20480
	ds_read_b64_tr_b16 v[144:145], v234 offset:20480
	v_cvt_pk_bf16_f32 v130, v222, v224
	v_mfma_f32_32x32x16_bf16 v[2:17], v[208:211], v[134:137], v[2:17]
	ds_read_b64_tr_b16 v[208:209], v237 offset:20480
	ds_read_b64_tr_b16 v[210:211], v250 offset:20480
	v_cvt_pk_bf16_f32 v134, v223, v225
	v_cvt_pk_bf16_f32 v135, v155, v227
	v_cvt_pk_bf16_f32 v136, v157, v229
	v_cvt_pk_bf16_f32 v137, v159, v161
	v_cvt_pk_bf16_f32 v131, v154, v226
	v_cvt_pk_bf16_f32 v132, v156, v228
	v_cvt_pk_bf16_f32 v133, v158, v160
	s_waitcnt lgkmcnt(6)
	v_mfma_f32_32x32x16_bf16 v[114:129], v[230:233], v[134:137], v[114:129]
	s_mov_b64 s[42:43], 0
	s_and_b64 vcc, exec, vcc
	v_mfma_f32_32x32x16_bf16 v[50:65], v[230:233], v[130:133], v[50:65]
	s_waitcnt lgkmcnt(0)
	v_mfma_f32_32x32x16_bf16 v[98:113], v[208:211], v[134:137], v[98:113]
	v_mfma_f32_32x32x16_bf16 v[34:49], v[208:211], v[130:133], v[34:49]
	v_mfma_f32_32x32x16_bf16 v[82:97], v[138:141], v[134:137], v[82:97]
	v_mfma_f32_32x32x16_bf16 v[18:33], v[138:141], v[130:133], v[18:33]
	v_add_f32_e64 v138, v214, v218
	v_add_f32_e64 v139, v215, v219
	v_add_f32_e64 v140, v216, v220
	v_add_f32_e64 v141, v217, v221
	v_add_f32_e64 v138, v138, v140
	v_add_f32_e64 v139, v139, v141
	v_mfma_f32_32x32x16_bf16 v[66:81], v[142:145], v[134:137], v[66:81]
	v_add_f32_e64 v134, v146, v150
	v_add_f32_e64 v135, v147, v151
	v_add_f32_e64 v136, v148, v152
	v_add_f32_e64 v137, v149, v153
	v_add_f32_e64 v146, v222, v224
	v_add_f32_e64 v147, v223, v225
	v_pk_add_f32 v[148:149], v[154:155], v[226:227]
	v_pk_add_f32 v[150:151], v[156:157], v[228:229]
	v_pk_add_f32 v[152:153], v[158:159], v[160:161]
	v_mfma_f32_32x32x16_bf16 v[2:17], v[142:145], v[130:133], v[2:17]
	v_add_f32_e64 v130, v134, v136
	v_add_f32_e64 v131, v135, v137
	v_add_f32_e64 v132, v146, v148
	v_add_f32_e64 v133, v147, v149
	v_add_f32_e64 v134, v150, v152
	v_add_f32_e64 v135, v151, v153
	v_pk_add_f32 v[130:131], v[138:139], v[130:131]
	v_pk_add_f32 v[132:133], v[132:133], v[134:135]
	s_nop 0
	v_pk_add_f32 v[130:131], v[130:131], v[132:133]
	s_nop 0
	v_pk_add_f32 v[212:213], v[212:213], v[130:131]
	s_cbranch_vccz .LBB0_48
; #define LAS __attribute__((address_space(3)))
; __device__ __forceinline__ float xsum32(float v) { const auto r = __builtin_amdgcn_permlane32_swap(__float_as_uint(v), __float_as_uint(v), false, false); return __uint_as_float(r[0]) + __uint_as_float(r[1]); }
; __device__ __forceinline__ void diff_attn_phase(const Params& p, LAS unsigned char* lds) {
;     ...
;         for (int ch = 0; ch < NCH; ++ch) {
;             if (ch + 1 < NCH) asm volatile("s_waitcnt vmcnt(4)" ::: "memory"); else asm volatile("s_waitcnt vmcnt(0)" ::: "memory");
;             __builtin_amdgcn_s_barrier(); asm volatile("" ::: "memory");
;             if (ch + 2 < NCH) issue(ch + 2, s_nn);
;             const LAS unsigned char* Ksb = lds + s_cur * STG; const LAS unsigned char* Vsb = Ksb + 16384;
;             s_nn = s_cur; s_cur = (s_cur == 2) ? 0 : s_cur + 1;
;     ...
;         float lam;
;         { const float* lv = p.diff_lambda; const float a = lv[lne] * lv[64 + lne], bb = lv[128 + lne] * lv[192 + lne]; const int xa = ((lne ^ 32) << 2); lam = __expf(wave_sum(a, xa)) - __expf(wave_sum(bb, xa)) + p.lam_init; }
; #pragma unroll
;         for (int r = 0; r < 2; ++r) {
;             __builtin_amdgcn_s_barrier(); asm volatile("" ::: "memory");
;             LAS float* ex = (LAS float*)lds + wq * 4096 + lne;
;             const float lt = xsum32(l[r]);
;             if (comp == 1) {
;                 const float sc = lam / lt;
; #pragma unroll
;                 for (int t = 0; t < 4; ++t)
; #pragma unroll
;                     for (int i = 0; i < 16; ++i) ex[(t * 16 + i) * 64] = O[r][t][i] * sc;
;             }
	s_add_i32 s29, s29, 1
	s_add_i32 s2, s34, 1
	s_cmp_lg_u32 s34, 2
	s_cselect_b32 s42, s2, 0
	s_cmpk_lg_i32 s29, 0x80
	s_cbranch_scc1 .LBB0_41
	v_mov_b32_e32 v130, v240
	v_readlane_b32 s92, v254, 42
	v_readlane_b32 s93, v254, 43
	v_ashrrev_i32_e32 v131, 31, v130
	s_load_dword s2, s[0:1], 0x220
	v_lshl_add_u64 v[132:133], v[130:131], 2, s[92:93]
	global_load_dword v1, v[132:133], off
	global_load_dword v131, v[132:133], off offset:256
	global_load_dword v134, v[132:133], off offset:512
	s_nop 0
	global_load_dword v132, v[132:133], off offset:768
	s_barrier
	s_and_b64 vcc, exec, s[44:45]
	v_readlane_b32 s94, v254, 44
	v_readlane_b32 s95, v254, 45
	s_waitcnt vmcnt(2)
	v_mul_f32_e32 v133, v1, v131
	ds_swizzle_b32 v133, v133 offset:swizzle(SWAP,1)
	s_waitcnt vmcnt(0)
	v_mul_f32_e32 v135, v134, v132
	ds_swizzle_b32 v135, v135 offset:swizzle(SWAP,1)
	s_waitcnt lgkmcnt(0)
	v_fmac_f32_e32 v133, v1, v131
	ds_swizzle_b32 v1, v133 offset:swizzle(SWAP,2)
	v_fmac_f32_e32 v135, v134, v132
	ds_swizzle_b32 v131, v135 offset:swizzle(SWAP,2)
	v_mov_b32_e32 v134, v213
	s_nop 1
	v_permlane32_swap_b32_e32 v213, v134
	s_waitcnt lgkmcnt(1)
	v_add_f32_e32 v1, v133, v1
	s_waitcnt lgkmcnt(0)
	v_add_f32_e32 v131, v135, v131
	ds_swizzle_b32 v132, v1 offset:swizzle(SWAP,4)
	ds_swizzle_b32 v133, v131 offset:swizzle(SWAP,4)
	v_lshlrev_b32_e32 v135, 2, v130
	v_xor_b32_e32 v136, 0x80, v135
	s_waitcnt lgkmcnt(1)
	v_add_f32_e32 v1, v1, v132
	s_waitcnt lgkmcnt(0)
	v_add_f32_e32 v131, v131, v133
	ds_swizzle_b32 v132, v1 offset:swizzle(SWAP,8)
	ds_swizzle_b32 v133, v131 offset:swizzle(SWAP,8)
	s_waitcnt lgkmcnt(1)
	v_add_f32_e32 v1, v1, v132
	s_waitcnt lgkmcnt(0)
	v_add_f32_e32 v131, v131, v133
	ds_swizzle_b32 v132, v1 offset:swizzle(SWAP,16)
	ds_swizzle_b32 v133, v131 offset:swizzle(SWAP,16)
	s_waitcnt lgkmcnt(1)
	v_add_f32_e32 v1, v1, v132
	s_waitcnt lgkmcnt(0)
	v_add_f32_e32 v131, v131, v133
	ds_bpermute_b32 v133, v136, v1
	ds_bpermute_b32 v136, v136, v131
	v_add_f32_e32 v132, v213, v134
	s_waitcnt lgkmcnt(1)
	v_add_f32_e32 v1, v1, v133
	s_waitcnt lgkmcnt(0)
	v_add_f32_e32 v131, v131, v136
	v_mul_f32_e32 v1, 0x3fb8aa3b, v1
	v_mul_f32_e32 v131, 0x3fb8aa3b, v131
	v_exp_f32_e32 v133, v1
	v_exp_f32_e32 v131, v131
	v_add_u32_e32 v1, s56, v135
	v_sub_f32_e32 v131, v133, v131
	v_add_f32_e32 v205, s2, v131
	s_cbranch_vccz .LBB0_52
	v_div_scale_f32 v131, s[10:11], v132, v132, v205
	v_rcp_f32_e32 v133, v131
	v_div_scale_f32 v134, vcc, v205, v132, v205
	v_fma_f32 v135, -v131, v133, 1.0
	v_fmac_f32_e32 v133, v135, v133
	v_mul_f32_e32 v135, v134, v133
	v_fma_f32 v136, -v131, v135, v134
	v_fmac_f32_e32 v135, v136, v133
	v_fma_f32 v131, -v131, v135, v134
	v_div_fmas_f32 v131, v131, v133, v135
	v_div_fixup_f32 v131, v131, v132, v205
	v_mul_f32_e32 v133, v114, v131
	v_mul_f32_e32 v134, v115, v131
	ds_write2st64_b32 v1, v133, v134 offset1:1
	v_mul_f32_e32 v133, v116, v131
	v_mul_f32_e32 v134, v117, v131
	ds_write2st64_b32 v1, v133, v134 offset0:2 offset1:3
	v_mul_f32_e32 v133, v118, v131
	v_mul_f32_e32 v134, v119, v131
	ds_write2st64_b32 v1, v133, v134 offset0:4 offset1:5
	v_mul_f32_e32 v133, v120, v131
	v_mul_f32_e32 v134, v121, v131
	ds_write2st64_b32 v1, v133, v134 offset0:6 offset1:7
	v_mul_f32_e32 v133, v122, v131
	v_mul_f32_e32 v134, v123, v131
	ds_write2st64_b32 v1, v133, v134 offset0:8 offset1:9
	v_mul_f32_e32 v133, v124, v131
	v_mul_f32_e32 v134, v125, v131
	ds_write2st64_b32 v1, v133, v134 offset0:10 offset1:11
	v_mul_f32_e32 v133, v126, v131
	v_mul_f32_e32 v134, v127, v131
	ds_write2st64_b32 v1, v133, v134 offset0:12 offset1:13
	v_mul_f32_e32 v133, v128, v131
	v_mul_f32_e32 v134, v129, v131
	ds_write2st64_b32 v1, v133, v134 offset0:14 offset1:15
	v_mul_f32_e32 v133, v98, v131
	v_mul_f32_e32 v134, v99, v131
	ds_write2st64_b32 v1, v133, v134 offset0:16 offset1:17
	v_mul_f32_e32 v133, v100, v131
	v_mul_f32_e32 v134, v101, v131
	ds_write2st64_b32 v1, v133, v134 offset0:18 offset1:19
	v_mul_f32_e32 v133, v102, v131
	v_mul_f32_e32 v134, v103, v131
	ds_write2st64_b32 v1, v133, v134 offset0:20 offset1:21
	v_mul_f32_e32 v133, v104, v131
	v_mul_f32_e32 v134, v105, v131
	ds_write2st64_b32 v1, v133, v134 offset0:22 offset1:23
	v_mul_f32_e32 v133, v106, v131
	v_mul_f32_e32 v134, v107, v131
	ds_write2st64_b32 v1, v133, v134 offset0:24 offset1:25
	v_mul_f32_e32 v133, v108, v131
	v_mul_f32_e32 v134, v109, v131
	ds_write2st64_b32 v1, v133, v134 offset0:26 offset1:27
	v_mul_f32_e32 v133, v110, v131
	v_mul_f32_e32 v134, v111, v131
	ds_write2st64_b32 v1, v133, v134 offset0:28 offset1:29
	v_mul_f32_e32 v133, v112, v131
	v_mul_f32_e32 v134, v113, v131
	ds_write2st64_b32 v1, v133, v134 offset0:30 offset1:31
	v_mul_f32_e32 v133, v82, v131
	v_mul_f32_e32 v134, v83, v131
	ds_write2st64_b32 v1, v133, v134 offset0:32 offset1:33
	v_mul_f32_e32 v133, v84, v131
	v_mul_f32_e32 v134, v85, v131
	ds_write2st64_b32 v1, v133, v134 offset0:34 offset1:35
	v_mul_f32_e32 v133, v86, v131
	v_mul_f32_e32 v134, v87, v131
	ds_write2st64_b32 v1, v133, v134 offset0:36 offset1:37
	v_mul_f32_e32 v133, v88, v131
	v_mul_f32_e32 v134, v89, v131
	ds_write2st64_b32 v1, v133, v134 offset0:38 offset1:39
	v_mul_f32_e32 v133, v90, v131
	v_mul_f32_e32 v134, v91, v131
	ds_write2st64_b32 v1, v133, v134 offset0:40 offset1:41
	v_mul_f32_e32 v133, v92, v131
	v_mul_f32_e32 v134, v93, v131
	ds_write2st64_b32 v1, v133, v134 offset0:42 offset1:43
	v_mul_f32_e32 v133, v94, v131
	v_mul_f32_e32 v134, v95, v131
	ds_write2st64_b32 v1, v133, v134 offset0:44 offset1:45
	v_mul_f32_e32 v133, v96, v131
	v_mul_f32_e32 v134, v97, v131
	ds_write2st64_b32 v1, v133, v134 offset0:46 offset1:47
	v_mul_f32_e32 v133, v66, v131
	v_mul_f32_e32 v134, v67, v131
	ds_write2st64_b32 v1, v133, v134 offset0:48 offset1:49
	v_mul_f32_e32 v133, v68, v131
	v_mul_f32_e32 v134, v69, v131
	ds_write2st64_b32 v1, v133, v134 offset0:50 offset1:51
	v_mul_f32_e32 v133, v70, v131
	v_mul_f32_e32 v134, v71, v131
	ds_write2st64_b32 v1, v133, v134 offset0:52 offset1:53
	v_mul_f32_e32 v133, v72, v131
	v_mul_f32_e32 v134, v73, v131
	ds_write2st64_b32 v1, v133, v134 offset0:54 offset1:55
	v_mul_f32_e32 v133, v74, v131
	v_mul_f32_e32 v134, v75, v131
	ds_write2st64_b32 v1, v133, v134 offset0:56 offset1:57
	v_mul_f32_e32 v133, v76, v131
	v_mul_f32_e32 v134, v77, v131
	ds_write2st64_b32 v1, v133, v134 offset0:58 offset1:59
	v_mul_f32_e32 v133, v78, v131
	v_mul_f32_e32 v134, v79, v131
	ds_write2st64_b32 v1, v133, v134 offset0:60 offset1:61
	v_mul_f32_e32 v133, v80, v131
	v_mul_f32_e32 v131, v81, v131
	ds_write2st64_b32 v1, v133, v131 offset0:62 offset1:63
